# gdn blocked solve: off-diagonal MFMA products of row blocks 2 and 3 fetch all six LDS fragments in one batch (were four serialized round trips each)
# baseline (speedup 1.0000x reference)
; #define LAS __attribute__((address_space(3)))
; #define LBAR() do { asm volatile("s_waitcnt lgkmcnt(0)" ::: "memory"); __builtin_amdgcn_s_barrier(); asm volatile("" ::: "memory"); } while (0)
; __device__ __forceinline__ void gdn_unit(const Ctx& X, LAS unsigned char* hl, int b, int c, int h, int tid_h, int w4, int lane, int layer) {
;     ...
;         if (I > 0) {
; #pragma unroll
;             for (int t2 = 0; t2 < 2; ++t2) { const int ct8 = 2 * w4 + t2; const LAS bf16_t* Bt = ct8 < 4 ? UT : WT;
;                 const f32x4 a = mma16(AB, 16 * I, Bt, 16 * (ct8 & 3), (f32x4){0.f, 0.f, 0.f, 0.f}, r, q);
; #pragma unroll
;                 for (int j = 0; j < 4; ++j) ACCS[(4 * q + j) * 128 + 16 * ct8 + r] = a[j]; }
;             LBAR();
;         }
;         if (w4 < 2) {
;             const int col = tid_h & 63, c128 = w4 * 64 + col;
;             float t[16];
; #pragma unroll
;             for (int ii = 0; ii < 16; ++ii) t[ii] = rc[16 * I + ii] - (I > 0 ? ACCS[ii * 128 + c128] : 0.f);
; #pragma unroll
;             for (int ii = 1; ii < 16; ++ii) {
;                 float a16[16];
;                 { float lo[8]; unpack8(*(const LAS u32x4*)(AB + (16 * I + ii) * LT + 16 * I), lo);
; #pragma unroll
;                   for (int e = 0; e < 8; ++e) a16[e] = lo[e]; }
;                 if (ii > 8) { float hi[8]; unpack8(*(const LAS u32x4*)(AB + (16 * I + ii) * LT + 16 * I + 8), hi);
; #pragma unroll
;                   for (int e = 0; e < 8; ++e) a16[8 + e] = hi[e]; }
;                 float s0 = t[ii], s1 = 0.f;
; #pragma unroll
;                 for (int kk = 0; kk < ii; ++kk) { if (kk & 1) s1 -= a16[kk] * t[kk]; else s0 -= a16[kk] * t[kk]; }
;                 t[ii] = s0 + s1;
;             }
.LBB0_615:
	s_waitcnt lgkmcnt(0)
	s_barrier
	ds_read_b128 v[72:75], v71 offset:4608
	ds_read_b128 v[76:79], v71 offset:4672
	ds_read_b128 v[80:83], v114
	ds_read_b128 v[48:51], v114 offset:64
	ds_read_b128 v[52:55], v115
	ds_read_b128 v[14:17], v115 offset:64
	s_and_b64 vcc, exec, s[4:5]
	s_waitcnt lgkmcnt(0)
	v_mfma_f32_16x16x32_bf16 v[6:9], v[72:75], v[80:83], 0
	v_mfma_f32_16x16x32_bf16 v[10:13], v[72:75], v[52:55], 0
	v_mfma_f32_16x16x32_bf16 v[6:9], v[76:79], v[48:51], v[6:9]
	v_mfma_f32_16x16x32_bf16 v[10:13], v[76:79], v[14:17], v[10:13]
	s_nop 7
	ds_write2st64_b32 v116, v6, v7 offset1:2
	ds_write2st64_b32 v116, v8, v9 offset0:4 offset1:6
	ds_write2st64_b32 v117, v10, v11 offset1:2
	ds_write2st64_b32 v117, v12, v13 offset0:4 offset1:6
	s_waitcnt lgkmcnt(0)
	s_barrier
	s_cbranch_vccnz .LBB0_617
	ds_read2st64_b32 v[6:7], v70 offset1:2
	ds_read2st64_b32 v[8:9], v70 offset0:4 offset1:6
	ds_read2st64_b32 v[10:11], v70 offset0:8 offset1:10
	ds_read2st64_b32 v[12:13], v70 offset0:12 offset1:14
	ds_read_b128 v[14:17], v186 offset:5104
	s_waitcnt lgkmcnt(4)
	v_sub_f32_e32 v7, v113, v7
	s_waitcnt lgkmcnt(3)
	v_sub_f32_e32 v36, v112, v8
	v_sub_f32_e32 v24, v111, v9
	ds_read2st64_b32 v[8:9], v70 offset0:16 offset1:18
	s_waitcnt lgkmcnt(3)
	v_sub_f32_e32 v32, v110, v10
	v_sub_f32_e32 v25, v109, v11
	s_waitcnt lgkmcnt(2)
	v_sub_f32_e32 v42, v108, v12
	v_sub_f32_e32 v26, v107, v13
	s_waitcnt lgkmcnt(0)
	v_sub_f32_e32 v46, v105, v8
	v_sub_f32_e32 v27, v104, v9
	ds_read2st64_b32 v[8:9], v70 offset0:28 offset1:30
	ds_read2st64_b32 v[10:11], v70 offset0:20 offset1:22
	ds_read2st64_b32 v[12:13], v70 offset0:24 offset1:26
	v_mov_b32_e32 v37, v157
	v_lshlrev_b32_e32 v15, 16, v15
	s_waitcnt lgkmcnt(2)
	v_sub_f32_e32 v156, v99, v8
	v_add_u32_e32 v8, 0x1000, v186
	ds_read2_b32 v[62:63], v8 offset0:180 offset1:216
	v_mov_b32_e32 v8, v9
	v_mov_b32_e32 v9, v6
	ds_read_b64 v[104:105], v186 offset:5248
	ds_read_b128 v[16:19], v186 offset:5392
	s_waitcnt lgkmcnt(4)
	v_sub_f32_e32 v52, v103, v10
	v_sub_f32_e32 v10, v102, v11
	s_waitcnt lgkmcnt(3)
	v_sub_f32_e32 v54, v101, v12
	v_sub_f32_e32 v11, v100, v13
	v_pk_add_f32 v[22:23], v[22:23], v[8:9] neg_lo:[0,1] neg_hi:[0,1]
	s_waitcnt lgkmcnt(2)
	v_lshlrev_b32_e32 v6, 16, v62
	ds_read_b96 v[150:152], v186 offset:5536
	ds_read_b128 v[100:103], v186 offset:5680
	v_fma_f32 v30, -v23, v6, v7
	ds_read_b128 v[108:111], v186 offset:5968
	ds_read_b128 v[118:121], v186 offset:5824
	v_lshlrev_b32_e32 v62, 16, v63
	v_and_b32_e32 v63, 0xffff0000, v63
	v_add_f32_e32 v201, 0, v30
	v_mov_b32_e32 v200, v23
	v_lshlrev_b32_e32 v6, 16, v14
	v_pk_fma_f32 v[36:37], v[200:201], v[62:63], v[36:37] neg_lo:[1,0,0] neg_hi:[1,0,0]
	v_fma_f32 v61, -v23, v6, v24
	s_waitcnt lgkmcnt(4)
	v_lshlrev_b32_e32 v6, 16, v16
	v_pk_add_f32 v[36:37], v[36:37], v[36:37] op_sel:[0,1] op_sel_hi:[1,0]
	v_fma_f32 v59, -v23, v6, v25
	s_waitcnt lgkmcnt(2)
	v_lshlrev_b32_e32 v6, 16, v100
	v_and_b32_e32 v14, 0xffff0000, v14
	v_mov_b32_e32 v62, v201
	v_mov_b32_e32 v63, v36
	v_mov_b32_e32 v60, v157
	v_fma_f32 v57, -v23, v6, v26
	s_waitcnt lgkmcnt(1)
	v_lshlrev_b32_e32 v6, 16, v108
	v_pk_fma_f32 v[14:15], v[62:63], v[14:15], v[60:61] neg_lo:[1,0,0] neg_hi:[1,0,0]
	v_fma_f32 v51, -v23, v6, v27
	v_add_u32_e32 v6, 0x1400, v186
	v_lshlrev_b32_e32 v196, 16, v104
	v_and_b32_e32 v197, 0xffff0000, v104
	v_mov_b32_e32 v33, v157
	v_pk_add_f32 v[14:15], v[14:15], v[14:15] op_sel:[0,1] op_sel_hi:[1,0]
	ds_read_b128 v[122:125], v186 offset:6112
	ds_read_b128 v[126:129], v186 offset:6256
	ds_read2_b32 v[112:113], v6 offset0:216 offset1:252
	ds_read_b128 v[134:137], v186 offset:6400
	v_lshlrev_b32_e32 v104, 16, v105
	v_and_b32_e32 v105, 0xffff0000, v105
	v_pk_fma_f32 v[32:33], v[200:201], v[196:197], v[32:33] neg_lo:[1,0,0] neg_hi:[1,0,0]
	v_mov_b32_e32 v37, v14
	v_pk_fma_f32 v[32:33], v[36:37], v[104:105], v[32:33] neg_lo:[1,0,0] neg_hi:[1,0,0]
	v_and_b32_e32 v198, 0xffff0000, v16
	v_lshlrev_b32_e32 v199, 16, v17
	v_pk_add_f32 v[32:33], v[32:33], v[32:33] op_sel:[0,1] op_sel_hi:[1,0]
	v_mov_b32_e32 v58, v157
	v_and_b32_e32 v16, 0xffff0000, v17
	v_lshlrev_b32_e32 v17, 16, v18
	v_pk_fma_f32 v[58:59], v[62:63], v[198:199], v[58:59] neg_lo:[1,0,0] neg_hi:[1,0,0]
	v_mov_b32_e32 v15, v32
	s_waitcnt lgkmcnt(1)
	v_lshlrev_b32_e32 v172, 16, v113
	v_and_b32_e32 v173, 0xffff0000, v113
	v_and_b32_e32 v190, 0xffff0000, v108
	v_lshlrev_b32_e32 v191, 16, v109
	v_and_b32_e32 v108, 0xffff0000, v109
	v_lshlrev_b32_e32 v109, 16, v110
	v_and_b32_e32 v192, 0xffff0000, v110
	v_lshlrev_b32_e32 v193, 16, v111
	v_and_b32_e32 v110, 0xffff0000, v111
	v_lshlrev_b32_e32 v111, 16, v112
	v_lshlrev_b32_e32 v112, 16, v150
	v_and_b32_e32 v113, 0xffff0000, v150
	v_mov_b32_e32 v43, v157
	v_pk_fma_f32 v[16:17], v[14:15], v[16:17], v[58:59] neg_lo:[1,0,0] neg_hi:[1,0,0]
	v_lshlrev_b32_e32 v6, 16, v126
	v_lshlrev_b32_e32 v150, 16, v151
	v_and_b32_e32 v151, 0xffff0000, v151
	v_pk_fma_f32 v[42:43], v[200:201], v[112:113], v[42:43] neg_lo:[1,0,0] neg_hi:[1,0,0]
	v_pk_add_f32 v[16:17], v[16:17], v[16:17] op_sel:[0,1] op_sel_hi:[1,0]
	v_fma_f32 v41, -v23, v6, v10
	ds_read_b128 v[138:141], v186 offset:6544
	v_add_u32_e32 v6, 0x1800, v186
	v_lshlrev_b32_e32 v194, 16, v152
	v_and_b32_e32 v195, 0xffff0000, v152
	v_pk_fma_f32 v[42:43], v[36:37], v[150:151], v[42:43] neg_lo:[1,0,0] neg_hi:[1,0,0]
	v_mov_b32_e32 v33, v16
	ds_read2_b64 v[142:145], v6 offset0:16 offset1:34
	ds_read_b128 v[6:9], v186 offset:6688
	ds_read_b128 v[146:149], v186 offset:6560
	ds_read_b96 v[48:50], v186 offset:6704
	v_and_b32_e32 v152, 0xffff0000, v100
	v_lshlrev_b32_e32 v153, 16, v101
	v_pk_fma_f32 v[42:43], v[32:33], v[194:195], v[42:43] neg_lo:[1,0,0] neg_hi:[1,0,0]
	v_mov_b32_e32 v56, v157
	v_and_b32_e32 v100, 0xffff0000, v101
	v_lshlrev_b32_e32 v101, 16, v102
	v_pk_add_f32 v[42:43], v[42:43], v[42:43] op_sel:[0,1] op_sel_hi:[1,0]
	v_pk_fma_f32 v[56:57], v[62:63], v[152:153], v[56:57] neg_lo:[1,0,0] neg_hi:[1,0,0]
	v_lshlrev_b32_e32 v178, 16, v118
	v_and_b32_e32 v179, 0xffff0000, v118
	v_mov_b32_e32 v47, v157
	v_and_b32_e32 v102, 0xffff0000, v102
	v_lshlrev_b32_e32 v103, 16, v103
	v_pk_fma_f32 v[56:57], v[14:15], v[100:101], v[56:57] neg_lo:[1,0,0] neg_hi:[1,0,0]
	v_mov_b32_e32 v17, v42
	v_lshlrev_b32_e32 v118, 16, v119
	v_and_b32_e32 v119, 0xffff0000, v119
	v_pk_fma_f32 v[46:47], v[200:201], v[178:179], v[46:47] neg_lo:[1,0,0] neg_hi:[1,0,0]
	v_pk_fma_f32 v[56:57], v[16:17], v[102:103], v[56:57] neg_lo:[1,0,0] neg_hi:[1,0,0]
	s_waitcnt lgkmcnt(4)
; #define LAS __attribute__((address_space(3)))
; __device__ __forceinline__ void gdn_unit(const Ctx& X, LAS unsigned char* hl, int b, int c, int h, int tid_h, int w4, int lane, int layer) {
;     ...
;             for (int ii = 1; ii < 16; ++ii) {
;                 float a16[16];
;                 { float lo[8]; unpack8(*(const LAS u32x4*)(AB + (16 * I + ii) * LT + 16 * I), lo);
; #pragma unroll
;                   for (int e = 0; e < 8; ++e) a16[e] = lo[e]; }
;                 if (ii > 8) { float hi[8]; unpack8(*(const LAS u32x4*)(AB + (16 * I + ii) * LT + 16 * I + 8), hi);
; #pragma unroll
;                   for (int e = 0; e < 8; ++e) a16[8 + e] = hi[e]; }
;                 float s0 = t[ii], s1 = 0.f;
; #pragma unroll
;                 for (int kk = 0; kk < ii; ++kk) { if (kk & 1) s1 -= a16[kk] * t[kk]; else s0 -= a16[kk] * t[kk]; }
;                 t[ii] = s0 + s1;
;             }
	v_lshlrev_b32_e32 v10, 16, v138
	v_lshlrev_b32_e32 v188, 16, v120
	v_and_b32_e32 v189, 0xffff0000, v120
	v_pk_add_f32 v[56:57], v[56:57], v[56:57] op_sel:[0,1] op_sel_hi:[1,0]
	v_pk_fma_f32 v[46:47], v[36:37], v[118:119], v[46:47] neg_lo:[1,0,0] neg_hi:[1,0,0]
	v_fma_f32 v31, -v23, v10, v11
	ds_read_b128 v[10:13], v186 offset:6832
	s_waitcnt lgkmcnt(1)
	v_lshlrev_b32_e32 v38, 16, v48
	v_and_b32_e32 v39, 0xffff0000, v48
	v_lshlrev_b32_e32 v44, 16, v49
	v_and_b32_e32 v45, 0xffff0000, v49
	v_lshlrev_b32_e32 v48, 16, v50
	v_and_b32_e32 v49, 0xffff0000, v50
	v_lshlrev_b32_e32 v120, 16, v121
	v_and_b32_e32 v121, 0xffff0000, v121
	v_pk_fma_f32 v[46:47], v[32:33], v[188:189], v[46:47] neg_lo:[1,0,0] neg_hi:[1,0,0]
	v_mov_b32_e32 v43, v56
	v_mov_b32_e32 v50, v157
	v_pk_fma_f32 v[46:47], v[42:43], v[120:121], v[46:47] neg_lo:[1,0,0] neg_hi:[1,0,0]
	v_pk_fma_f32 v[50:51], v[62:63], v[190:191], v[50:51] neg_lo:[1,0,0] neg_hi:[1,0,0]
	v_and_b32_e32 v164, 0xffff0000, v138
	v_lshlrev_b32_e32 v165, 16, v139
	v_and_b32_e32 v138, 0xffff0000, v139
	v_lshlrev_b32_e32 v139, 16, v140
	v_and_b32_e32 v166, 0xffff0000, v140
	v_lshlrev_b32_e32 v167, 16, v141
	v_and_b32_e32 v140, 0xffff0000, v141
	v_lshlrev_b32_e32 v141, 16, v146
	v_and_b32_e32 v168, 0xffff0000, v146
	v_lshlrev_b32_e32 v169, 16, v147
	v_and_b32_e32 v146, 0xffff0000, v147
	v_lshlrev_b32_e32 v147, 16, v148
	v_lshlrev_b32_e32 v148, 16, v122
	v_and_b32_e32 v149, 0xffff0000, v122
	v_mov_b32_e32 v53, v157
	v_pk_add_f32 v[46:47], v[46:47], v[46:47] op_sel:[0,1] op_sel_hi:[1,0]
	v_pk_fma_f32 v[50:51], v[14:15], v[108:109], v[50:51] neg_lo:[1,0,0] neg_hi:[1,0,0]
	v_lshlrev_b32_e32 v122, 16, v123
	v_and_b32_e32 v123, 0xffff0000, v123
	v_pk_fma_f32 v[52:53], v[200:201], v[148:149], v[52:53] neg_lo:[1,0,0] neg_hi:[1,0,0]
	v_pk_fma_f32 v[50:51], v[16:17], v[192:193], v[50:51] neg_lo:[1,0,0] neg_hi:[1,0,0]
	v_mov_b32_e32 v57, v46
	v_lshlrev_b32_e32 v170, 16, v124
	v_and_b32_e32 v171, 0xffff0000, v124
	v_pk_fma_f32 v[50:51], v[56:57], v[110:111], v[50:51] neg_lo:[1,0,0] neg_hi:[1,0,0]
	v_pk_fma_f32 v[52:53], v[36:37], v[122:123], v[52:53] neg_lo:[1,0,0] neg_hi:[1,0,0]
	v_lshlrev_b32_e32 v124, 16, v125
	v_and_b32_e32 v125, 0xffff0000, v125
	v_and_b32_e32 v174, 0xffff0000, v126
	v_lshlrev_b32_e32 v175, 16, v127
	v_pk_add_f32 v[50:51], v[50:51], v[50:51] op_sel:[0,1] op_sel_hi:[1,0]
	v_pk_fma_f32 v[52:53], v[32:33], v[170:171], v[52:53] neg_lo:[1,0,0] neg_hi:[1,0,0]
	v_mov_b32_e32 v40, v157
	v_and_b32_e32 v126, 0xffff0000, v127
	v_lshlrev_b32_e32 v127, 16, v128
	v_pk_fma_f32 v[52:53], v[42:43], v[124:125], v[52:53] neg_lo:[1,0,0] neg_hi:[1,0,0]
	v_mov_b32_e32 v47, v50
	v_pk_fma_f32 v[40:41], v[62:63], v[174:175], v[40:41] neg_lo:[1,0,0] neg_hi:[1,0,0]
	v_lshlrev_b32_e32 v162, 16, v134
	v_and_b32_e32 v163, 0xffff0000, v134
	v_mov_b32_e32 v55, v157
	v_and_b32_e32 v176, 0xffff0000, v128
	v_lshlrev_b32_e32 v177, 16, v129
	v_pk_fma_f32 v[52:53], v[46:47], v[172:173], v[52:53] neg_lo:[1,0,0] neg_hi:[1,0,0]
	v_pk_fma_f32 v[40:41], v[14:15], v[126:127], v[40:41] neg_lo:[1,0,0] neg_hi:[1,0,0]
	v_lshlrev_b32_e32 v64, 16, v135
	v_and_b32_e32 v65, 0xffff0000, v135
	v_and_b32_e32 v128, 0xffff0000, v129
	v_lshlrev_b32_e32 v129, 16, v142
	v_pk_fma_f32 v[54:55], v[200:201], v[162:163], v[54:55] neg_lo:[1,0,0] neg_hi:[1,0,0]
	v_pk_add_f32 v[52:53], v[52:53], v[52:53] op_sel:[0,1] op_sel_hi:[1,0]
	v_pk_fma_f32 v[40:41], v[16:17], v[176:177], v[40:41] neg_lo:[1,0,0] neg_hi:[1,0,0]
	v_lshlrev_b32_e32 v66, 16, v136
	v_and_b32_e32 v67, 0xffff0000, v136
	v_and_b32_e32 v142, 0xffff0000, v142
	v_lshlrev_b32_e32 v143, 16, v143
	v_pk_fma_f32 v[40:41], v[56:57], v[128:129], v[40:41] neg_lo:[1,0,0] neg_hi:[1,0,0]
	v_mov_b32_e32 v51, v52
	v_pk_fma_f32 v[54:55], v[36:37], v[64:65], v[54:55] neg_lo:[1,0,0] neg_hi:[1,0,0]
	v_lshlrev_b32_e32 v134, 16, v137
	v_and_b32_e32 v135, 0xffff0000, v137
	v_pk_fma_f32 v[40:41], v[50:51], v[142:143], v[40:41] neg_lo:[1,0,0] neg_hi:[1,0,0]
	v_pk_fma_f32 v[54:55], v[32:33], v[66:67], v[54:55] neg_lo:[1,0,0] neg_hi:[1,0,0]
	v_mov_b32_e32 v30, v157
	v_lshlrev_b32_e32 v136, 16, v144
	v_and_b32_e32 v137, 0xffff0000, v144
	v_pk_add_f32 v[40:41], v[40:41], v[40:41] op_sel:[0,1] op_sel_hi:[1,0]
	v_pk_fma_f32 v[54:55], v[42:43], v[134:135], v[54:55] neg_lo:[1,0,0] neg_hi:[1,0,0]
	v_pk_fma_f32 v[30:31], v[62:63], v[164:165], v[30:31] neg_lo:[1,0,0] neg_hi:[1,0,0]
	v_lshlrev_b32_e32 v24, 16, v6
	v_and_b32_e32 v25, 0xffff0000, v6
	v_lshlrev_b32_e32 v144, 16, v145
	v_and_b32_e32 v145, 0xffff0000, v145
	v_pk_fma_f32 v[54:55], v[46:47], v[136:137], v[54:55] neg_lo:[1,0,0] neg_hi:[1,0,0]
	v_mov_b32_e32 v53, v40
	v_pk_fma_f32 v[30:31], v[14:15], v[138:139], v[30:31] neg_lo:[1,0,0] neg_hi:[1,0,0]
	v_lshlrev_b32_e32 v26, 16, v7
	v_and_b32_e32 v27, 0xffff0000, v7
	v_lshlrev_b32_e32 v28, 16, v8
	v_and_b32_e32 v29, 0xffff0000, v8
	v_lshlrev_b32_e32 v34, 16, v9
	v_and_b32_e32 v35, 0xffff0000, v9
	ds_read_b128 v[6:9], v186 offset:6848
	v_pk_fma_f32 v[54:55], v[52:53], v[144:145], v[54:55] neg_lo:[1,0,0] neg_hi:[1,0,0]
	v_pk_fma_f32 v[30:31], v[16:17], v[166:167], v[30:31] neg_lo:[1,0,0] neg_hi:[1,0,0]
	v_pk_fma_f32 v[24:25], v[200:201], v[24:25], v[156:157] neg_lo:[1,0,0] neg_hi:[1,0,0]
	s_waitcnt lgkmcnt(1)
; #define LAS __attribute__((address_space(3)))
; __device__ __forceinline__ unsigned pk2(float lo, float hi) { return pg8::cvt_pk_bf16(lo, hi); }
; #define LBAR() do { asm volatile("s_waitcnt lgkmcnt(0)" ::: "memory"); __builtin_amdgcn_s_barrier(); asm volatile("" ::: "memory"); } while (0)
; __device__ __forceinline__ void gdn_unit(const Ctx& X, LAS unsigned char* hl, int b, int c, int h, int tid_h, int w4, int lane, int layer) {
;     ...
;         if (I > 0) {
; #pragma unroll
;             for (int t2 = 0; t2 < 2; ++t2) { const int ct8 = 2 * w4 + t2; const LAS bf16_t* Bt = ct8 < 4 ? UT : WT;
;                 const f32x4 a = mma16(AB, 16 * I, Bt, 16 * (ct8 & 3), (f32x4){0.f, 0.f, 0.f, 0.f}, r, q);
; #pragma unroll
;                 for (int j = 0; j < 4; ++j) ACCS[(4 * q + j) * 128 + 16 * ct8 + r] = a[j]; }
;             LBAR();
;         }
;         if (w4 < 2) {
;             const int col = tid_h & 63, c128 = w4 * 64 + col;
;             float t[16];
; #pragma unroll
;             for (int ii = 0; ii < 16; ++ii) t[ii] = rc[16 * I + ii] - (I > 0 ? ACCS[ii * 128 + c128] : 0.f);
; #pragma unroll
;             for (int ii = 1; ii < 16; ++ii) {
;                 float a16[16];
;                 { float lo[8]; unpack8(*(const LAS u32x4*)(AB + (16 * I + ii) * LT + 16 * I), lo);
; #pragma unroll
;                   for (int e = 0; e < 8; ++e) a16[e] = lo[e]; }
;                 if (ii > 8) { float hi[8]; unpack8(*(const LAS u32x4*)(AB + (16 * I + ii) * LT + 16 * I + 8), hi);
; #pragma unroll
;                   for (int e = 0; e < 8; ++e) a16[8 + e] = hi[e]; }
;                 float s0 = t[ii], s1 = 0.f;
; #pragma unroll
;                 for (int kk = 0; kk < ii; ++kk) { if (kk & 1) s1 -= a16[kk] * t[kk]; else s0 -= a16[kk] * t[kk]; }
;                 t[ii] = s0 + s1;
;             }
;             LAS bf16_t* dst = (w4 == 0 ? UT : WT) + col * LT + 16 * I;
;             u32x4 w0, w1;
;             w0.x = pk2(t[0], t[1]); w0.y = pk2(t[2], t[3]); w0.z = pk2(t[4], t[5]); w0.w = pk2(t[6], t[7]);
;             w1.x = pk2(t[8], t[9]); w1.y = pk2(t[10], t[11]); w1.z = pk2(t[12], t[13]); w1.w = pk2(t[14], t[15]);
;             *(LAS u32x4*)dst = w0; *(LAS u32x4*)(dst + 8) = w1;
	v_lshlrev_b32_e32 v19, 16, v10
	v_pk_add_f32 v[54:55], v[54:55], v[54:55] op_sel:[0,1] op_sel_hi:[1,0]
	v_pk_fma_f32 v[30:31], v[56:57], v[140:141], v[30:31] neg_lo:[1,0,0] neg_hi:[1,0,0]
	v_pk_fma_f32 v[24:25], v[36:37], v[26:27], v[24:25] neg_lo:[1,0,0] neg_hi:[1,0,0]
	v_fma_f32 v19, -v23, v19, v22
	v_pk_fma_f32 v[30:31], v[50:51], v[168:169], v[30:31] neg_lo:[1,0,0] neg_hi:[1,0,0]
	v_mov_b32_e32 v41, v54
	v_pk_fma_f32 v[24:25], v[32:33], v[28:29], v[24:25] neg_lo:[1,0,0] neg_hi:[1,0,0]
	v_and_b32_e32 v26, 0xffff0000, v10
	v_lshlrev_b32_e32 v27, 16, v11
	v_mov_b32_e32 v18, v157
	v_pk_fma_f32 v[30:31], v[40:41], v[146:147], v[30:31] neg_lo:[1,0,0] neg_hi:[1,0,0]
	v_pk_fma_f32 v[24:25], v[42:43], v[34:35], v[24:25] neg_lo:[1,0,0] neg_hi:[1,0,0]
	v_and_b32_e32 v10, 0xffff0000, v11
	v_lshlrev_b32_e32 v11, 16, v12
	v_pk_fma_f32 v[18:19], v[62:63], v[26:27], v[18:19] neg_lo:[1,0,0] neg_hi:[1,0,0]
	v_pk_add_f32 v[30:31], v[30:31], v[30:31] op_sel:[0,1] op_sel_hi:[1,0]
	v_pk_fma_f32 v[24:25], v[46:47], v[38:39], v[24:25] neg_lo:[1,0,0] neg_hi:[1,0,0]
	v_and_b32_e32 v28, 0xffff0000, v12
	v_lshlrev_b32_e32 v29, 16, v13
	v_pk_fma_f32 v[10:11], v[14:15], v[10:11], v[18:19] neg_lo:[1,0,0] neg_hi:[1,0,0]
	v_pk_fma_f32 v[24:25], v[52:53], v[44:45], v[24:25] neg_lo:[1,0,0] neg_hi:[1,0,0]
	v_mov_b32_e32 v55, v30
	v_and_b32_e32 v12, 0xffff0000, v13
	s_waitcnt lgkmcnt(0)
	v_lshlrev_b32_e32 v13, 16, v6
	v_pk_fma_f32 v[10:11], v[16:17], v[28:29], v[10:11] neg_lo:[1,0,0] neg_hi:[1,0,0]
	v_pk_fma_f32 v[24:25], v[54:55], v[48:49], v[24:25] neg_lo:[1,0,0] neg_hi:[1,0,0]
	v_and_b32_e32 v34, 0xffff0000, v6
	v_lshlrev_b32_e32 v35, 16, v7
	v_pk_fma_f32 v[10:11], v[56:57], v[12:13], v[10:11] neg_lo:[1,0,0] neg_hi:[1,0,0]
	v_pk_add_f32 v[24:25], v[24:25], v[24:25] op_sel:[0,1] op_sel_hi:[1,0]
	v_and_b32_e32 v6, 0xffff0000, v7
	v_lshlrev_b32_e32 v7, 16, v8
	v_pk_fma_f32 v[10:11], v[50:51], v[34:35], v[10:11] neg_lo:[1,0,0] neg_hi:[1,0,0]
	v_and_b32_e32 v8, 0xffff0000, v8
	v_lshlrev_b32_e32 v9, 16, v9
	v_pk_fma_f32 v[6:7], v[40:41], v[6:7], v[10:11] neg_lo:[1,0,0] neg_hi:[1,0,0]
	v_mov_b32_e32 v31, v24
	v_pk_fma_f32 v[6:7], v[30:31], v[8:9], v[6:7] neg_lo:[1,0,0] neg_hi:[1,0,0]
	s_nop 0
	v_add_f32_e32 v13, v6, v7
	v_cvt_pk_bf16_f32 v6, v23, v201
	v_cvt_pk_bf16_f32 v7, v36, v14
	v_cvt_pk_bf16_f32 v8, v32, v16
	v_cvt_pk_bf16_f32 v9, v42, v56
	v_cvt_pk_bf16_f32 v10, v46, v50
	v_cvt_pk_bf16_f32 v11, v52, v40
	v_cvt_pk_bf16_f32 v12, v54, v30
	v_cvt_pk_bf16_f32 v13, v24, v13
	ds_write_b128 v84, v[6:9] offset:64
	ds_write_b128 v84, v[10:13] offset:80
.LBB0_617:
	s_waitcnt lgkmcnt(0)
	s_barrier
	ds_read_b128 v[72:75], v71 offset:6912
	ds_read_b128 v[76:79], v71 offset:6976
	ds_read_b128 v[80:83], v114
	ds_read_b128 v[48:51], v114 offset:64
	ds_read_b128 v[52:55], v115
	ds_read_b128 v[14:17], v115 offset:64
	s_and_b64 vcc, exec, s[4:5]
	s_waitcnt lgkmcnt(0)
	v_mfma_f32_16x16x32_bf16 v[6:9], v[72:75], v[80:83], 0
	v_mfma_f32_16x16x32_bf16 v[10:13], v[72:75], v[52:55], 0
	v_mfma_f32_16x16x32_bf16 v[6:9], v[76:79], v[48:51], v[6:9]
	v_mfma_f32_16x16x32_bf16 v[10:13], v[76:79], v[14:17], v[10:13]
	s_nop 7
	ds_write2st64_b32 v116, v6, v7 offset1:2
	ds_write2st64_b32 v116, v8, v9 offset0:4 offset1:6
	ds_write2st64_b32 v117, v10, v11 offset1:2
	ds_write2st64_b32 v117, v12, v13 offset0:4 offset1:6
	s_waitcnt lgkmcnt(0)
	s_barrier
	s_cbranch_vccnz .LBB0_619
	ds_read2st64_b32 v[6:7], v70 offset1:2
	ds_read2st64_b32 v[8:9], v70 offset0:4 offset1:6
	ds_read2st64_b32 v[10:11], v70 offset0:8 offset1:10
	ds_read2st64_b32 v[12:13], v70 offset0:12 offset1:14
	ds_read_b128 v[14:17], v186 offset:7440
	s_waitcnt lgkmcnt(4)
	v_sub_f32_e32 v7, v98, v7
	s_waitcnt lgkmcnt(3)
	v_sub_f32_e32 v34, v97, v8
	v_sub_f32_e32 v22, v96, v9
	ds_read2st64_b32 v[8:9], v70 offset0:16 offset1:18
	s_waitcnt lgkmcnt(3)
	v_sub_f32_e32 v30, v95, v10
	v_sub_f32_e32 v23, v94, v11
	s_waitcnt lgkmcnt(2)
	v_sub_f32_e32 v38, v93, v12
	v_sub_f32_e32 v24, v92, v13
	s_waitcnt lgkmcnt(0)
	v_sub_f32_e32 v42, v91, v8
	v_sub_f32_e32 v25, v90, v9
	ds_read2st64_b32 v[8:9], v70 offset0:28 offset1:30
	ds_read2st64_b32 v[10:11], v70 offset0:20 offset1:22
	ds_read2st64_b32 v[12:13], v70 offset0:24 offset1:26
	v_mov_b32_e32 v35, v157
	v_lshlrev_b32_e32 v15, 16, v15
	s_waitcnt lgkmcnt(2)
	v_sub_f32_e32 v156, v85, v8
	v_add_u32_e32 v8, 0x1a00, v186
	ds_read2_b32 v[58:59], v8 offset0:124 offset1:160
	ds_read_b64 v[70:71], v186 offset:7584
	ds_read_b128 v[64:67], v186 offset:7728
	v_mov_b32_e32 v8, v9
	v_mov_b32_e32 v9, v6
	s_waitcnt lgkmcnt(4)
	v_sub_f32_e32 v48, v89, v10
	v_sub_f32_e32 v10, v88, v11
	s_waitcnt lgkmcnt(3)
	v_sub_f32_e32 v50, v87, v12
	v_sub_f32_e32 v11, v86, v13
	v_pk_add_f32 v[18:19], v[20:21], v[8:9] neg_lo:[0,1] neg_hi:[0,1]
	s_waitcnt lgkmcnt(2)
	v_lshlrev_b32_e32 v6, 16, v58
	ds_read_b96 v[124:126], v186 offset:7872
	ds_read_b128 v[86:89], v186 offset:8016
	v_fma_f32 v16, -v19, v6, v7
	v_lshlrev_b32_e32 v6, 16, v14
	v_fma_f32 v57, -v19, v6, v22
	s_waitcnt lgkmcnt(2)
	v_lshlrev_b32_e32 v6, 16, v64
	ds_read_b128 v[90:93], v186 offset:8304
	ds_read_b128 v[94:97], v186 offset:8160
	v_and_b32_e32 v170, 0xffff0000, v64
	v_lshlrev_b32_e32 v171, 16, v65
	v_and_b32_e32 v64, 0xffff0000, v65
	v_lshlrev_b32_e32 v65, 16, v66
	v_lshlrev_b32_e32 v58, 16, v59
	v_and_b32_e32 v59, 0xffff0000, v59
	v_add_f32_e32 v67, 0, v16
	v_mov_b32_e32 v66, v19
	v_pk_fma_f32 v[34:35], v[66:67], v[58:59], v[34:35] neg_lo:[1,0,0] neg_hi:[1,0,0]
	v_fma_f32 v55, -v19, v6, v23
	v_pk_add_f32 v[34:35], v[34:35], v[34:35] op_sel:[0,1] op_sel_hi:[1,0]
	s_waitcnt lgkmcnt(2)
; #define LAS __attribute__((address_space(3)))
; __device__ __forceinline__ void gdn_unit(const Ctx& X, LAS unsigned char* hl, int b, int c, int h, int tid_h, int w4, int lane, int layer) {
;     ...
;             for (int ii = 1; ii < 16; ++ii) {
;                 float a16[16];
;                 { float lo[8]; unpack8(*(const LAS u32x4*)(AB + (16 * I + ii) * LT + 16 * I), lo);
; #pragma unroll
;                   for (int e = 0; e < 8; ++e) a16[e] = lo[e]; }
;                 if (ii > 8) { float hi[8]; unpack8(*(const LAS u32x4*)(AB + (16 * I + ii) * LT + 16 * I + 8), hi);
; #pragma unroll
;                   for (int e = 0; e < 8; ++e) a16[8 + e] = hi[e]; }
;                 float s0 = t[ii], s1 = 0.f;
; #pragma unroll
;                 for (int kk = 0; kk < ii; ++kk) { if (kk & 1) s1 -= a16[kk] * t[kk]; else s0 -= a16[kk] * t[kk]; }
;                 t[ii] = s0 + s1;
;             }
	v_lshlrev_b32_e32 v6, 16, v86
	v_and_b32_e32 v14, 0xffff0000, v14
	v_mov_b32_e32 v58, v67
	v_mov_b32_e32 v59, v34
	v_mov_b32_e32 v56, v157
	v_fma_f32 v53, -v19, v6, v24
	s_waitcnt lgkmcnt(1)
	v_lshlrev_b32_e32 v6, 16, v90
	v_pk_fma_f32 v[14:15], v[58:59], v[14:15], v[56:57] neg_lo:[1,0,0] neg_hi:[1,0,0]
	v_fma_f32 v47, -v19, v6, v25
	v_add_u32_e32 v6, 0x2000, v186
	v_lshlrev_b32_e32 v168, 16, v70
	v_and_b32_e32 v169, 0xffff0000, v70
	v_mov_b32_e32 v31, v157
	v_pk_add_f32 v[14:15], v[14:15], v[14:15] op_sel:[0,1] op_sel_hi:[1,0]
	ds_read_b128 v[98:101], v186 offset:8448
	ds_read_b128 v[102:105], v186 offset:8592
	ds_read2_b32 v[128:129], v6 offset0:32 offset1:68
	ds_read_b128 v[108:111], v186 offset:8736
	v_lshlrev_b32_e32 v70, 16, v71
	v_and_b32_e32 v71, 0xffff0000, v71
	v_pk_fma_f32 v[30:31], v[66:67], v[168:169], v[30:31] neg_lo:[1,0,0] neg_hi:[1,0,0]
	v_mov_b32_e32 v35, v14
	v_pk_fma_f32 v[30:31], v[34:35], v[70:71], v[30:31] neg_lo:[1,0,0] neg_hi:[1,0,0]
	v_mov_b32_e32 v54, v157
	v_pk_add_f32 v[30:31], v[30:31], v[30:31] op_sel:[0,1] op_sel_hi:[1,0]
	v_pk_fma_f32 v[54:55], v[58:59], v[170:171], v[54:55] neg_lo:[1,0,0] neg_hi:[1,0,0]
	v_mov_b32_e32 v15, v30
	s_waitcnt lgkmcnt(1)
	v_lshlrev_b32_e32 v144, 16, v129
	v_and_b32_e32 v145, 0xffff0000, v129
	v_and_b32_e32 v162, 0xffff0000, v90
	v_lshlrev_b32_e32 v163, 16, v91
	v_and_b32_e32 v90, 0xffff0000, v91
	v_lshlrev_b32_e32 v91, 16, v92
	v_and_b32_e32 v164, 0xffff0000, v92
	v_lshlrev_b32_e32 v165, 16, v93
	v_and_b32_e32 v92, 0xffff0000, v93
	v_lshlrev_b32_e32 v93, 16, v128
	v_lshlrev_b32_e32 v128, 16, v124
	v_and_b32_e32 v129, 0xffff0000, v124
	v_mov_b32_e32 v39, v157
	v_pk_fma_f32 v[54:55], v[14:15], v[64:65], v[54:55] neg_lo:[1,0,0] neg_hi:[1,0,0]
	v_lshlrev_b32_e32 v124, 16, v125
	v_and_b32_e32 v125, 0xffff0000, v125
	v_pk_fma_f32 v[38:39], v[66:67], v[128:129], v[38:39] neg_lo:[1,0,0] neg_hi:[1,0,0]
	v_pk_add_f32 v[54:55], v[54:55], v[54:55] op_sel:[0,1] op_sel_hi:[1,0]
	v_lshlrev_b32_e32 v7, 16, v102
	ds_read_b128 v[112:115], v186 offset:8880
	v_lshlrev_b32_e32 v166, 16, v126
	v_and_b32_e32 v167, 0xffff0000, v126
	v_pk_fma_f32 v[38:39], v[34:35], v[124:125], v[38:39] neg_lo:[1,0,0] neg_hi:[1,0,0]
	v_mov_b32_e32 v31, v54
	v_fma_f32 v41, -v19, v7, v10
	ds_read2_b64 v[116:119], v6 offset0:52 offset1:70
	ds_read_b128 v[6:9], v186 offset:9024
	ds_read_b128 v[120:123], v186 offset:8896
	ds_read_b96 v[44:46], v186 offset:9040
	v_and_b32_e32 v126, 0xffff0000, v86
	v_lshlrev_b32_e32 v127, 16, v87
	v_pk_fma_f32 v[38:39], v[30:31], v[166:167], v[38:39] neg_lo:[1,0,0] neg_hi:[1,0,0]
	v_mov_b32_e32 v52, v157
	v_and_b32_e32 v86, 0xffff0000, v87
	v_lshlrev_b32_e32 v87, 16, v88
	v_pk_add_f32 v[38:39], v[38:39], v[38:39] op_sel:[0,1] op_sel_hi:[1,0]
	v_pk_fma_f32 v[52:53], v[58:59], v[126:127], v[52:53] neg_lo:[1,0,0] neg_hi:[1,0,0]
	v_lshlrev_b32_e32 v150, 16, v94
	v_and_b32_e32 v151, 0xffff0000, v94
	v_mov_b32_e32 v43, v157
	v_and_b32_e32 v88, 0xffff0000, v88
	v_lshlrev_b32_e32 v89, 16, v89
	v_pk_fma_f32 v[52:53], v[14:15], v[86:87], v[52:53] neg_lo:[1,0,0] neg_hi:[1,0,0]
	v_mov_b32_e32 v55, v38
	v_lshlrev_b32_e32 v94, 16, v95
	v_and_b32_e32 v95, 0xffff0000, v95
	v_pk_fma_f32 v[42:43], v[66:67], v[150:151], v[42:43] neg_lo:[1,0,0] neg_hi:[1,0,0]
	v_pk_fma_f32 v[52:53], v[54:55], v[88:89], v[52:53] neg_lo:[1,0,0] neg_hi:[1,0,0]
	s_waitcnt lgkmcnt(4)
	v_lshlrev_b32_e32 v10, 16, v112
	v_lshlrev_b32_e32 v152, 16, v96
	v_and_b32_e32 v153, 0xffff0000, v96
	v_pk_add_f32 v[52:53], v[52:53], v[52:53] op_sel:[0,1] op_sel_hi:[1,0]
	v_pk_fma_f32 v[42:43], v[34:35], v[94:95], v[42:43] neg_lo:[1,0,0] neg_hi:[1,0,0]
	v_fma_f32 v27, -v19, v10, v11
	ds_read_b128 v[10:13], v186 offset:9168
	s_waitcnt lgkmcnt(1)
	v_lshlrev_b32_e32 v32, 16, v44
	v_and_b32_e32 v33, 0xffff0000, v44
	v_lshlrev_b32_e32 v36, 16, v45
	v_and_b32_e32 v37, 0xffff0000, v45
	v_lshlrev_b32_e32 v44, 16, v46
	v_and_b32_e32 v45, 0xffff0000, v46
	v_lshlrev_b32_e32 v96, 16, v97
	v_and_b32_e32 v97, 0xffff0000, v97
	v_pk_fma_f32 v[42:43], v[30:31], v[152:153], v[42:43] neg_lo:[1,0,0] neg_hi:[1,0,0]
	v_mov_b32_e32 v39, v52
	v_mov_b32_e32 v46, v157
	v_pk_fma_f32 v[42:43], v[38:39], v[96:97], v[42:43] neg_lo:[1,0,0] neg_hi:[1,0,0]
	v_pk_fma_f32 v[46:47], v[58:59], v[162:163], v[46:47] neg_lo:[1,0,0] neg_hi:[1,0,0]
	v_and_b32_e32 v136, 0xffff0000, v112
	v_lshlrev_b32_e32 v137, 16, v113
	v_and_b32_e32 v112, 0xffff0000, v113
	v_lshlrev_b32_e32 v113, 16, v114
	v_and_b32_e32 v138, 0xffff0000, v114
	v_lshlrev_b32_e32 v139, 16, v115
	v_and_b32_e32 v114, 0xffff0000, v115
	v_lshlrev_b32_e32 v115, 16, v120
	v_and_b32_e32 v140, 0xffff0000, v120
	v_lshlrev_b32_e32 v141, 16, v121
	v_and_b32_e32 v120, 0xffff0000, v121
	v_lshlrev_b32_e32 v121, 16, v122
	v_lshlrev_b32_e32 v122, 16, v98
	v_and_b32_e32 v123, 0xffff0000, v98
	v_mov_b32_e32 v49, v157
	v_pk_add_f32 v[42:43], v[42:43], v[42:43] op_sel:[0,1] op_sel_hi:[1,0]
	v_pk_fma_f32 v[46:47], v[14:15], v[90:91], v[46:47] neg_lo:[1,0,0] neg_hi:[1,0,0]
	v_lshlrev_b32_e32 v98, 16, v99
	v_and_b32_e32 v99, 0xffff0000, v99
	v_pk_fma_f32 v[48:49], v[66:67], v[122:123], v[48:49] neg_lo:[1,0,0] neg_hi:[1,0,0]
	v_pk_fma_f32 v[46:47], v[54:55], v[164:165], v[46:47] neg_lo:[1,0,0] neg_hi:[1,0,0]
	v_mov_b32_e32 v53, v42
	v_lshlrev_b32_e32 v142, 16, v100
	v_and_b32_e32 v143, 0xffff0000, v100
	v_pk_fma_f32 v[46:47], v[52:53], v[92:93], v[46:47] neg_lo:[1,0,0] neg_hi:[1,0,0]
	v_pk_fma_f32 v[48:49], v[34:35], v[98:99], v[48:49] neg_lo:[1,0,0] neg_hi:[1,0,0]
	v_lshlrev_b32_e32 v100, 16, v101
	v_and_b32_e32 v101, 0xffff0000, v101
	v_and_b32_e32 v146, 0xffff0000, v102
	v_lshlrev_b32_e32 v147, 16, v103
; #define LAS __attribute__((address_space(3)))
; __device__ __forceinline__ unsigned pk2(float lo, float hi) { return pg8::cvt_pk_bf16(lo, hi); }
; __device__ __forceinline__ void gdn_unit(const Ctx& X, LAS unsigned char* hl, int b, int c, int h, int tid_h, int w4, int lane, int layer) {
;     ...
;             for (int ii = 1; ii < 16; ++ii) {
;                 float a16[16];
;                 { float lo[8]; unpack8(*(const LAS u32x4*)(AB + (16 * I + ii) * LT + 16 * I), lo);
; #pragma unroll
;                   for (int e = 0; e < 8; ++e) a16[e] = lo[e]; }
;                 if (ii > 8) { float hi[8]; unpack8(*(const LAS u32x4*)(AB + (16 * I + ii) * LT + 16 * I + 8), hi);
; #pragma unroll
;                   for (int e = 0; e < 8; ++e) a16[8 + e] = hi[e]; }
;                 float s0 = t[ii], s1 = 0.f;
; #pragma unroll
;                 for (int kk = 0; kk < ii; ++kk) { if (kk & 1) s1 -= a16[kk] * t[kk]; else s0 -= a16[kk] * t[kk]; }
;                 t[ii] = s0 + s1;
;             }
;             LAS bf16_t* dst = (w4 == 0 ? UT : WT) + col * LT + 16 * I;
;             u32x4 w0, w1;
;             w0.x = pk2(t[0], t[1]); w0.y = pk2(t[2], t[3]); w0.z = pk2(t[4], t[5]); w0.w = pk2(t[6], t[7]);
;             w1.x = pk2(t[8], t[9]); w1.y = pk2(t[10], t[11]); w1.z = pk2(t[12], t[13]); w1.w = pk2(t[14], t[15]);
;             *(LAS u32x4*)dst = w0; *(LAS u32x4*)(dst + 8) = w1;
	v_pk_add_f32 v[46:47], v[46:47], v[46:47] op_sel:[0,1] op_sel_hi:[1,0]
	v_pk_fma_f32 v[48:49], v[30:31], v[142:143], v[48:49] neg_lo:[1,0,0] neg_hi:[1,0,0]
	v_mov_b32_e32 v40, v157
	v_and_b32_e32 v102, 0xffff0000, v103
	v_lshlrev_b32_e32 v103, 16, v104
	v_pk_fma_f32 v[48:49], v[38:39], v[100:101], v[48:49] neg_lo:[1,0,0] neg_hi:[1,0,0]
	v_mov_b32_e32 v43, v46
	v_pk_fma_f32 v[40:41], v[58:59], v[146:147], v[40:41] neg_lo:[1,0,0] neg_hi:[1,0,0]
	v_lshlrev_b32_e32 v134, 16, v108
	v_and_b32_e32 v135, 0xffff0000, v108
	v_mov_b32_e32 v51, v157
	v_and_b32_e32 v148, 0xffff0000, v104
	v_lshlrev_b32_e32 v149, 16, v105
	v_pk_fma_f32 v[48:49], v[42:43], v[144:145], v[48:49] neg_lo:[1,0,0] neg_hi:[1,0,0]
	v_pk_fma_f32 v[40:41], v[14:15], v[102:103], v[40:41] neg_lo:[1,0,0] neg_hi:[1,0,0]
	v_lshlrev_b32_e32 v60, 16, v109
	v_and_b32_e32 v61, 0xffff0000, v109
	v_and_b32_e32 v104, 0xffff0000, v105
	v_lshlrev_b32_e32 v105, 16, v116
	v_pk_fma_f32 v[50:51], v[66:67], v[134:135], v[50:51] neg_lo:[1,0,0] neg_hi:[1,0,0]
	v_pk_add_f32 v[48:49], v[48:49], v[48:49] op_sel:[0,1] op_sel_hi:[1,0]
	v_pk_fma_f32 v[40:41], v[54:55], v[148:149], v[40:41] neg_lo:[1,0,0] neg_hi:[1,0,0]
	v_lshlrev_b32_e32 v62, 16, v110
	v_and_b32_e32 v63, 0xffff0000, v110
	v_and_b32_e32 v116, 0xffff0000, v116
	v_lshlrev_b32_e32 v117, 16, v117
	v_pk_fma_f32 v[40:41], v[52:53], v[104:105], v[40:41] neg_lo:[1,0,0] neg_hi:[1,0,0]
	v_mov_b32_e32 v47, v48
	v_pk_fma_f32 v[50:51], v[34:35], v[60:61], v[50:51] neg_lo:[1,0,0] neg_hi:[1,0,0]
	v_lshlrev_b32_e32 v108, 16, v111
	v_and_b32_e32 v109, 0xffff0000, v111
	v_pk_fma_f32 v[40:41], v[46:47], v[116:117], v[40:41] neg_lo:[1,0,0] neg_hi:[1,0,0]
	v_pk_fma_f32 v[50:51], v[30:31], v[62:63], v[50:51] neg_lo:[1,0,0] neg_hi:[1,0,0]
	v_mov_b32_e32 v26, v157
	v_lshlrev_b32_e32 v110, 16, v118
	v_and_b32_e32 v111, 0xffff0000, v118
	v_pk_add_f32 v[40:41], v[40:41], v[40:41] op_sel:[0,1] op_sel_hi:[1,0]
	v_pk_fma_f32 v[50:51], v[38:39], v[108:109], v[50:51] neg_lo:[1,0,0] neg_hi:[1,0,0]
	v_pk_fma_f32 v[26:27], v[58:59], v[136:137], v[26:27] neg_lo:[1,0,0] neg_hi:[1,0,0]
	v_lshlrev_b32_e32 v20, 16, v6
	v_and_b32_e32 v21, 0xffff0000, v6
	v_lshlrev_b32_e32 v118, 16, v119
	v_and_b32_e32 v119, 0xffff0000, v119
	v_pk_fma_f32 v[50:51], v[42:43], v[110:111], v[50:51] neg_lo:[1,0,0] neg_hi:[1,0,0]
	v_mov_b32_e32 v49, v40
	v_pk_fma_f32 v[26:27], v[14:15], v[112:113], v[26:27] neg_lo:[1,0,0] neg_hi:[1,0,0]
	v_lshlrev_b32_e32 v22, 16, v7
	v_and_b32_e32 v23, 0xffff0000, v7
	v_lshlrev_b32_e32 v24, 16, v8
	v_and_b32_e32 v25, 0xffff0000, v8
	v_lshlrev_b32_e32 v28, 16, v9
	v_and_b32_e32 v29, 0xffff0000, v9
	ds_read_b128 v[6:9], v186 offset:9184
	v_pk_fma_f32 v[50:51], v[48:49], v[118:119], v[50:51] neg_lo:[1,0,0] neg_hi:[1,0,0]
	v_pk_fma_f32 v[26:27], v[54:55], v[138:139], v[26:27] neg_lo:[1,0,0] neg_hi:[1,0,0]
	v_pk_fma_f32 v[20:21], v[66:67], v[20:21], v[156:157] neg_lo:[1,0,0] neg_hi:[1,0,0]
	s_waitcnt lgkmcnt(1)
	v_lshlrev_b32_e32 v17, 16, v10
	v_pk_add_f32 v[50:51], v[50:51], v[50:51] op_sel:[0,1] op_sel_hi:[1,0]
	v_pk_fma_f32 v[26:27], v[52:53], v[114:115], v[26:27] neg_lo:[1,0,0] neg_hi:[1,0,0]
	v_pk_fma_f32 v[20:21], v[34:35], v[22:23], v[20:21] neg_lo:[1,0,0] neg_hi:[1,0,0]
	v_fma_f32 v17, -v19, v17, v18
	v_pk_fma_f32 v[26:27], v[46:47], v[140:141], v[26:27] neg_lo:[1,0,0] neg_hi:[1,0,0]
	v_mov_b32_e32 v41, v50
	v_pk_fma_f32 v[20:21], v[30:31], v[24:25], v[20:21] neg_lo:[1,0,0] neg_hi:[1,0,0]
	v_and_b32_e32 v22, 0xffff0000, v10
	v_lshlrev_b32_e32 v23, 16, v11
	v_mov_b32_e32 v16, v157
	v_pk_fma_f32 v[26:27], v[40:41], v[120:121], v[26:27] neg_lo:[1,0,0] neg_hi:[1,0,0]
	v_pk_fma_f32 v[20:21], v[38:39], v[28:29], v[20:21] neg_lo:[1,0,0] neg_hi:[1,0,0]
	v_and_b32_e32 v10, 0xffff0000, v11
	v_lshlrev_b32_e32 v11, 16, v12
	v_pk_fma_f32 v[16:17], v[58:59], v[22:23], v[16:17] neg_lo:[1,0,0] neg_hi:[1,0,0]
	v_pk_add_f32 v[26:27], v[26:27], v[26:27] op_sel:[0,1] op_sel_hi:[1,0]
	v_pk_fma_f32 v[20:21], v[42:43], v[32:33], v[20:21] neg_lo:[1,0,0] neg_hi:[1,0,0]
	v_and_b32_e32 v24, 0xffff0000, v12
	v_lshlrev_b32_e32 v25, 16, v13
	v_pk_fma_f32 v[10:11], v[14:15], v[10:11], v[16:17] neg_lo:[1,0,0] neg_hi:[1,0,0]
	v_pk_fma_f32 v[20:21], v[48:49], v[36:37], v[20:21] neg_lo:[1,0,0] neg_hi:[1,0,0]
	v_mov_b32_e32 v51, v26
	v_and_b32_e32 v12, 0xffff0000, v13
	s_waitcnt lgkmcnt(0)
	v_lshlrev_b32_e32 v13, 16, v6
	v_pk_fma_f32 v[10:11], v[54:55], v[24:25], v[10:11] neg_lo:[1,0,0] neg_hi:[1,0,0]
	v_pk_fma_f32 v[20:21], v[50:51], v[44:45], v[20:21] neg_lo:[1,0,0] neg_hi:[1,0,0]
	v_and_b32_e32 v28, 0xffff0000, v6
	v_lshlrev_b32_e32 v29, 16, v7
	v_pk_fma_f32 v[10:11], v[52:53], v[12:13], v[10:11] neg_lo:[1,0,0] neg_hi:[1,0,0]
	v_pk_add_f32 v[20:21], v[20:21], v[20:21] op_sel:[0,1] op_sel_hi:[1,0]
	v_and_b32_e32 v6, 0xffff0000, v7
	v_lshlrev_b32_e32 v7, 16, v8
	v_pk_fma_f32 v[10:11], v[46:47], v[28:29], v[10:11] neg_lo:[1,0,0] neg_hi:[1,0,0]
	v_and_b32_e32 v8, 0xffff0000, v8
	v_lshlrev_b32_e32 v9, 16, v9
	v_pk_fma_f32 v[6:7], v[40:41], v[6:7], v[10:11] neg_lo:[1,0,0] neg_hi:[1,0,0]
	v_mov_b32_e32 v27, v20
	v_pk_fma_f32 v[6:7], v[26:27], v[8:9], v[6:7] neg_lo:[1,0,0] neg_hi:[1,0,0]
	s_nop 0
	v_add_f32_e32 v13, v6, v7
	v_cvt_pk_bf16_f32 v6, v19, v67
	v_cvt_pk_bf16_f32 v7, v34, v14
	v_cvt_pk_bf16_f32 v8, v30, v54
	v_cvt_pk_bf16_f32 v9, v38, v52
	v_cvt_pk_bf16_f32 v10, v42, v46
	v_cvt_pk_bf16_f32 v11, v48, v40
	v_cvt_pk_bf16_f32 v12, v50, v26
	v_cvt_pk_bf16_f32 v13, v20, v13
	ds_write_b128 v84, v[6:9] offset:96
	ds_write_b128 v84, v[10:13] offset:112
; __device__ __forceinline__ float bf2f(bf16_t b) { return __uint_as_float((unsigned)b << 16); }
; __device__ __forceinline__ bf16_t f2bf(float f) { return (bf16_t)(pk2(f, 0.f) & 0xffffu); }
; __device__ __forceinline__ float fexp(float x) { return __expf(x); }
; __device__ __forceinline__ void gdn_unit(const Ctx& X, LAS unsigned char* hl, int b, int c, int h, int tid_h, int w4, int lane, int layer) {
;     ...
;     {
;         f32x4 acc[4];
;         const float eG63 = fexp(Gs[63]);
; #pragma unroll
;         for (int ct = 0; ct < 4; ++ct) acc[ct] = mma16(P, 16 * w4, WT, 16 * ct, (f32x4){0.f, 0.f, 0.f, 0.f}, r, q);
;         bf16_t* qe = WSP(bf16_t, WS_QEFF) + (size_t)uid * 4096;
; #pragma unroll
;         for (int ct = 0; ct < 4; ++ct)
; #pragma unroll
;             for (int j = 0; j < 4; ++j) { const int ii = 16 * w4 + 4 * q + j, col = 16 * ct + r;
;                 qe[ii * 64 + col] = f2bf(bf2f(Q[ii * LT + col]) * fexp(Gs[ii]) - acc[ct][j]); }
; #pragma unroll
;         for (int ct = 0; ct < 4; ++ct) acc[ct] = mma16(P, 16 * w4, UT, 16 * ct, (f32x4){0.f, 0.f, 0.f, 0.f}, r, q);
;         store_oloc(WSP(bf16_t, WS_OLOC), uid, w4, lane, acc);
; #pragma unroll
;         for (int ct = 0; ct < 4; ++ct) acc[ct] = mma16(KDT, 16 * w4, WT, 16 * ct, (f32x4){0.f, 0.f, 0.f, 0.f}, r, q);
;         bf16_t* mm = WSP(bf16_t, WS_MM) + (size_t)(uid - 2048) * 4096;
; #pragma unroll
;         for (int ct = 0; ct < 4; ++ct)
; #pragma unroll
;             for (int j = 0; j < 4; ++j) { const int ii = 16 * w4 + 4 * q + j, col = 16 * ct + r;
;                 mm[((w4 * 2 + (ct >> 1)) * 64 + (r >> 2) * 16 + 4 * q + j) * 8 + (ct & 1) * 4 + (r & 3)] = f2bf((ii == col ? eG63 : 0.f) - acc[ct][j]); }
; #pragma unroll
;         for (int ct = 0; ct < 4; ++ct) acc[ct] = mma16(KDT, 16 * w4, UT, 16 * ct, (f32x4){0.f, 0.f, 0.f, 0.f}, r, q);
.LBB0_619:
	s_waitcnt lgkmcnt(0)
	s_barrier
	v_bfe_u32 v54, v224, 6, 2
	v_and_b32_e32 v55, 15, v232
	v_lshrrev_b32_e32 v56, 4, v232
	v_lshl_or_b32 v57, v54, 4, v55
	v_mul_u32_u24_e32 v58, 0x90, v57
	v_mul_u32_u24_e32 v59, 0x90, v55
	v_lshl_add_u32 v60, v56, 4, v58
	v_lshl_add_u32 v61, v56, 4, v59
	v_add_u32_e32 v60, v182, v60
	v_add_u32_e32 v61, v182, v61
	v_add_u32_e32 v178, 0xb400, v60
	v_add_u32_e32 v179, 0x4800, v61
	v_add_u32_e32 v60, 0x9000, v60
	v_add_u32_e32 v61, 0x6c00, v61
	ds_read_b128 v[6:9], v178
	ds_read_b128 v[10:13], v178 offset:64
	ds_read_b128 v[22:25], v179
	ds_read_b128 v[26:29], v179 offset:64
	ds_read_b128 v[30:33], v179 offset:2304
	ds_read_b128 v[34:37], v179 offset:2368
	ds_read_b128 v[38:41], v179 offset:4608
	ds_read_b128 v[42:45], v179 offset:4672
	ds_read_b128 v[46:49], v179 offset:6912
	ds_read_b128 v[50:53], v179 offset:6976
	ds_read_b128 v[14:17], v60
	ds_read_b128 v[18:21], v60 offset:64
	v_lshl_add_u32 v62, v57, 2, v185
	v_lshl_add_u32 v63, v56, 3, v58
	v_add_u32_e32 v63, v182, v63
	ds_read_b32 v176, v62
	ds_read_b32 v177, v185 offset:252
	s_lshl_b32 s0, s22, 9
	s_lshl_b32 s1, s23, 7
	s_add_i32 s1, s1, s0
	s_or_b32 s0, s1, s21
	s_ashr_i32 s1, s0, 31
	s_lshl_b64 s[0:1], s[0:1], 13
	s_add_u32 s4, s89, s0
	s_addc_u32 s5, s78, s1
	s_add_u32 s6, s79, s0
	s_addc_u32 s7, s80, s1
	v_readlane_b32 s98, v253, 3
	v_readlane_b32 s99, v253, 4
	s_add_u32 s98, s98, s0
	s_addc_u32 s99, s99, s1
	s_add_u32 s98, s98, 0xff000000
	s_addc_u32 s99, s99, -1
	s_add_u32 s100, s74, s0
	s_addc_u32 s101, s75, s1
	v_readfirstlane_b32 s32, v54
	v_lshlrev_b32_e32 v64, 11, v54
	v_lshlrev_b32_e32 v65, 5, v232
	v_lshl_add_u32 v64, v232, 4, v64
	v_lshlrev_b32_e32 v66, 9, v54
	v_lshl_add_u32 v66, v232, 3, v66
	v_add_u32_e32 v67, 0x1000, v66
	v_lshlrev_b32_e32 v71, 7, v57
	v_lshl_add_u32 v71, v56, 3, v71
	v_lshlrev_b32_e32 v70, 2, v56
	v_sub_u32_e32 v70, v55, v70
	s_waitcnt lgkmcnt(4)
	v_mfma_f32_16x16x32_bf16 v[134:137], v[22:25], v[6:9], 0
	v_mfma_f32_16x16x32_bf16 v[138:141], v[30:33], v[6:9], 0
	v_mfma_f32_16x16x32_bf16 v[142:145], v[38:41], v[6:9], 0
	v_mfma_f32_16x16x32_bf16 v[146:149], v[46:49], v[6:9], 0
	v_mfma_f32_16x16x32_bf16 v[134:137], v[26:29], v[10:13], v[134:137]
	v_mfma_f32_16x16x32_bf16 v[138:141], v[34:37], v[10:13], v[138:141]
	v_mfma_f32_16x16x32_bf16 v[142:145], v[42:45], v[10:13], v[142:145]
	v_mfma_f32_16x16x32_bf16 v[146:149], v[50:53], v[10:13], v[146:149]
	ds_read_b64 v[150:151], v63
	ds_read_b64 v[152:153], v63 offset:32
	ds_read_b64 v[172:173], v63 offset:64
	ds_read_b64 v[174:175], v63 offset:96
	ds_read_b128 v[186:189], v61
	ds_read_b128 v[190:193], v61 offset:64
	ds_read_b128 v[194:197], v61 offset:2304
	ds_read_b128 v[198:201], v61 offset:2368
	ds_read_b128 v[202:205], v61 offset:4608
	ds_read_b128 v[206:209], v61 offset:4672
	ds_read_b128 v[210:213], v61 offset:6912
	s_waitcnt lgkmcnt(13)
	v_mfma_f32_16x16x32_bf16 v[236:239], v[22:25], v[14:17], 0
	v_mfma_f32_16x16x32_bf16 v[240:243], v[30:33], v[14:17], 0
	v_mfma_f32_16x16x32_bf16 v[244:247], v[38:41], v[14:17], 0
	v_mfma_f32_16x16x32_bf16 v[248:251], v[46:49], v[14:17], 0
	v_mfma_f32_16x16x32_bf16 v[236:239], v[26:29], v[18:21], v[236:239]
	v_mfma_f32_16x16x32_bf16 v[240:243], v[34:37], v[18:21], v[240:243]
	v_mfma_f32_16x16x32_bf16 v[244:247], v[42:45], v[18:21], v[244:247]
	v_mfma_f32_16x16x32_bf16 v[248:251], v[50:53], v[18:21], v[248:251]
	ds_read_b128 v[214:217], v61 offset:6976
	s_waitcnt lgkmcnt(8)
	v_mul_f32_e32 v176, 0x3fb8aa3b, v176
	v_mul_f32_e32 v177, 0x3fb8aa3b, v177
	v_exp_f32_e32 v176, v176
	v_exp_f32_e32 v177, v177
	v_cmp_eq_u32_e32 vcc, 0, v70
	v_cmp_eq_u32_e64 s[0:1], 1, v70
	v_lshlrev_b32_e32 v76, 16, v150
	v_and_b32_e32 v77, 0xffff0000, v150
	v_cndmask_b32_e32 v72, 0, v177, vcc
	v_cndmask_b32_e64 v73, 0, v177, s[0:1]
	v_cmp_eq_u32_e32 vcc, 2, v70
	v_cmp_eq_u32_e64 s[0:1], 3, v70
	v_lshlrev_b32_e32 v78, 16, v151
	v_and_b32_e32 v79, 0xffff0000, v151
	v_cndmask_b32_e32 v74, 0, v177, vcc
	v_cndmask_b32_e64 v75, 0, v177, s[0:1]
	s_waitcnt lgkmcnt(0)
; __device__ __forceinline__ float bf2f(bf16_t b) { return __uint_as_float((unsigned)b << 16); }
; __device__ __forceinline__ bf16_t f2bf(float f) { return (bf16_t)(pk2(f, 0.f) & 0xffffu); }
; __device__ __forceinline__ float fexp(float x) { return __expf(x); }
; __device__ __forceinline__ void gdn_unit(const Ctx& X, LAS unsigned char* hl, int b, int c, int h, int tid_h, int w4, int lane, int layer) {
;     ...
;         bf16_t* qe = WSP(bf16_t, WS_QEFF) + (size_t)uid * 4096;
; #pragma unroll
;         for (int ct = 0; ct < 4; ++ct)
; #pragma unroll
;             for (int j = 0; j < 4; ++j) { const int ii = 16 * w4 + 4 * q + j, col = 16 * ct + r;
;                 qe[ii * 64 + col] = f2bf(bf2f(Q[ii * LT + col]) * fexp(Gs[ii]) - acc[ct][j]); }
; #pragma unroll
;         for (int ct = 0; ct < 4; ++ct) acc[ct] = mma16(P, 16 * w4, UT, 16 * ct, (f32x4){0.f, 0.f, 0.f, 0.f}, r, q);
;         store_oloc(WSP(bf16_t, WS_OLOC), uid, w4, lane, acc);
; #pragma unroll
;         for (int ct = 0; ct < 4; ++ct) acc[ct] = mma16(KDT, 16 * w4, WT, 16 * ct, (f32x4){0.f, 0.f, 0.f, 0.f}, r, q);
;         bf16_t* mm = WSP(bf16_t, WS_MM) + (size_t)(uid - 2048) * 4096;
; #pragma unroll
;         for (int ct = 0; ct < 4; ++ct)
; #pragma unroll
;             for (int j = 0; j < 4; ++j) { const int ii = 16 * w4 + 4 * q + j, col = 16 * ct + r;
;                 mm[((w4 * 2 + (ct >> 1)) * 64 + (r >> 2) * 16 + 4 * q + j) * 8 + (ct & 1) * 4 + (r & 3)] = f2bf((ii == col ? eG63 : 0.f) - acc[ct][j]); }
; #pragma unroll
;         for (int ct = 0; ct < 4; ++ct) acc[ct] = mma16(KDT, 16 * w4, UT, 16 * ct, (f32x4){0.f, 0.f, 0.f, 0.f}, r, q);
;         store_bc(WSP(bf16_t, WS_BCS), uid, w4, r, q, acc);
	v_mfma_f32_16x16x32_bf16 v[84:87], v[6:9], v[186:189], 0
	v_mfma_f32_16x16x32_bf16 v[88:91], v[6:9], v[194:197], 0
	v_mfma_f32_16x16x32_bf16 v[92:95], v[6:9], v[202:205], 0
	v_mfma_f32_16x16x32_bf16 v[96:99], v[6:9], v[210:213], 0
	v_mfma_f32_16x16x32_bf16 v[114:117], v[14:17], v[186:189], 0
	v_mfma_f32_16x16x32_bf16 v[118:121], v[14:17], v[194:197], 0
	v_mfma_f32_16x16x32_bf16 v[122:125], v[14:17], v[202:205], 0
	v_mfma_f32_16x16x32_bf16 v[126:129], v[14:17], v[210:213], 0
	v_mfma_f32_16x16x32_bf16 v[84:87], v[10:13], v[190:193], v[84:87]
	v_mfma_f32_16x16x32_bf16 v[88:91], v[10:13], v[198:201], v[88:91]
	v_mfma_f32_16x16x32_bf16 v[92:95], v[10:13], v[206:209], v[92:95]
	v_mfma_f32_16x16x32_bf16 v[96:99], v[10:13], v[214:217], v[96:99]
	v_mfma_f32_16x16x32_bf16 v[114:117], v[18:21], v[190:193], v[114:117]
	v_mfma_f32_16x16x32_bf16 v[118:121], v[18:21], v[198:201], v[118:121]
	v_mfma_f32_16x16x32_bf16 v[122:125], v[18:21], v[206:209], v[122:125]
	v_mfma_f32_16x16x32_bf16 v[126:129], v[18:21], v[214:217], v[126:129]
	v_fma_f32 v76, v176, v76, -v134
	v_fma_f32 v77, v176, v77, -v135
	v_fma_f32 v78, v176, v78, -v136
	v_fma_f32 v79, v176, v79, -v137
	v_cvt_pk_bf16_f32 v218, v76, v77
	v_cvt_pk_bf16_f32 v219, v78, v79
	global_store_dwordx2 v71, v[218:219], s[4:5]
	v_lshlrev_b32_e32 v76, 16, v152
	v_and_b32_e32 v77, 0xffff0000, v152
	v_lshlrev_b32_e32 v78, 16, v153
	v_and_b32_e32 v79, 0xffff0000, v153
	v_fma_f32 v76, v176, v76, -v138
	v_fma_f32 v77, v176, v77, -v139
	v_fma_f32 v78, v176, v78, -v140
	v_fma_f32 v79, v176, v79, -v141
	v_cvt_pk_bf16_f32 v220, v76, v77
	v_cvt_pk_bf16_f32 v221, v78, v79
	global_store_dwordx2 v71, v[220:221], s[4:5] offset:32
	v_lshlrev_b32_e32 v76, 16, v172
	v_and_b32_e32 v77, 0xffff0000, v172
	v_lshlrev_b32_e32 v78, 16, v173
	v_and_b32_e32 v79, 0xffff0000, v173
	v_fma_f32 v76, v176, v76, -v142
	v_fma_f32 v77, v176, v77, -v143
	v_fma_f32 v78, v176, v78, -v144
	v_fma_f32 v79, v176, v79, -v145
	v_cvt_pk_bf16_f32 v222, v76, v77
	v_cvt_pk_bf16_f32 v223, v78, v79
	global_store_dwordx2 v71, v[222:223], s[4:5] offset:64
	v_lshlrev_b32_e32 v76, 16, v174
	v_and_b32_e32 v77, 0xffff0000, v174
	v_lshlrev_b32_e32 v78, 16, v175
	v_and_b32_e32 v79, 0xffff0000, v175
	v_fma_f32 v76, v176, v76, -v146
	v_fma_f32 v77, v176, v77, -v147
	v_fma_f32 v78, v176, v78, -v148
	v_fma_f32 v79, v176, v79, -v149
	v_cvt_pk_bf16_f32 v226, v76, v77
	v_cvt_pk_bf16_f32 v227, v78, v79
	global_store_dwordx2 v71, v[226:227], s[4:5] offset:96
	s_cmp_eq_u32 s32, 0
	s_cselect_b32 s0, 1.0, 0
	v_fma_f32 v76, v72, s0, -v236
	v_fma_f32 v77, v73, s0, -v237
	v_fma_f32 v78, v74, s0, -v238
	v_fma_f32 v79, v75, s0, -v239
	v_cvt_pk_bf16_f32 v100, v76, v77
	v_cvt_pk_bf16_f32 v101, v78, v79
	s_cmp_eq_u32 s32, 1
	s_cselect_b32 s0, 1.0, 0
	v_fma_f32 v76, v72, s0, -v240
	v_fma_f32 v77, v73, s0, -v241
	v_fma_f32 v78, v74, s0, -v242
	v_fma_f32 v79, v75, s0, -v243
	v_cvt_pk_bf16_f32 v102, v76, v77
	v_cvt_pk_bf16_f32 v103, v78, v79
	global_store_dwordx4 v64, v[100:103], s[98:99]
	s_cmp_eq_u32 s32, 2
	s_cselect_b32 s0, 1.0, 0
	v_fma_f32 v76, v72, s0, -v244
	v_fma_f32 v77, v73, s0, -v245
	v_fma_f32 v78, v74, s0, -v246
	v_fma_f32 v79, v75, s0, -v247
	v_cvt_pk_bf16_f32 v104, v76, v77
	v_cvt_pk_bf16_f32 v105, v78, v79
	s_cmp_eq_u32 s32, 3
	s_cselect_b32 s0, 1.0, 0
	v_fma_f32 v76, v72, s0, -v248
	v_fma_f32 v77, v73, s0, -v249
	v_fma_f32 v78, v74, s0, -v250
	v_fma_f32 v79, v75, s0, -v251
	v_cvt_pk_bf16_f32 v106, v76, v77
	v_cvt_pk_bf16_f32 v107, v78, v79
	global_store_dwordx4 v64, v[104:107], s[98:99] offset:1024
	v_cvt_pk_bf16_f32 v108, v84, v85
	v_cvt_pk_bf16_f32 v109, v86, v87
	v_cvt_pk_bf16_f32 v110, v88, v89
	v_cvt_pk_bf16_f32 v111, v90, v91
	global_store_dwordx4 v65, v[108:111], s[6:7] nt
	v_cvt_pk_bf16_f32 v80, v92, v93
	v_cvt_pk_bf16_f32 v81, v94, v95
	v_cvt_pk_bf16_f32 v82, v96, v97
	v_cvt_pk_bf16_f32 v83, v98, v99
	global_store_dwordx4 v65, v[80:83], s[6:7] offset:16 nt
	v_cvt_pk_bf16_f32 v40, v114, v115
	v_cvt_pk_bf16_f32 v41, v116, v117
	global_store_dwordx2 v66, v[40:41], s[100:101]
	v_cvt_pk_bf16_f32 v42, v118, v119
	v_cvt_pk_bf16_f32 v43, v120, v121
	global_store_dwordx2 v66, v[42:43], s[100:101] offset:2048
	v_cvt_pk_bf16_f32 v44, v122, v123
	v_cvt_pk_bf16_f32 v45, v124, v125
	global_store_dwordx2 v67, v[44:45], s[100:101]
	v_cvt_pk_bf16_f32 v46, v126, v127
	v_cvt_pk_bf16_f32 v47, v128, v129
	global_store_dwordx2 v67, v[46:47], s[100:101] offset:2048
	s_branch .Lgdn_p4_pad_end
	s_nop 0
	s_nop 0
	s_nop 0
	s_nop 0
	s_nop 0
	s_nop 0
	s_nop 0
	s_nop 0
	s_nop 0
	s_nop 0
	s_nop 0
	s_nop 0
	s_nop 0
	s_nop 0
	s_nop 0
	s_nop 0
	s_nop 0
	s_nop 0
	s_nop 0
	s_nop 0
	s_nop 0
	s_nop 0
	s_nop 0
	s_nop 0
	s_nop 0
	s_nop 0
	s_nop 0
	s_nop 0
	s_nop 0
	s_nop 0
	s_nop 0
	s_nop 0
	s_nop 0
	s_nop 0
	s_nop 0
	s_nop 0
	s_nop 0
	s_nop 0
	s_nop 0
	s_nop 0
	s_nop 0
	s_nop 0
	s_nop 0
	s_nop 0
	s_nop 0
	s_nop 0
	s_nop 0
	s_nop 0
	s_nop 0
	s_nop 0
	s_nop 0
	s_nop 0
	s_nop 0
	s_nop 0
	s_nop 0
	s_nop 0
	s_nop 0
	s_nop 0
	s_nop 0
	s_nop 0
	s_nop 0
	s_nop 0
	s_nop 0
	s_nop 0
	s_nop 0
	s_nop 0
	s_nop 0
	s_nop 0
	s_nop 0
	s_nop 0
	s_nop 0
	s_nop 0
	s_nop 0
	s_nop 0
	s_nop 0
	s_nop 0
	s_nop 0
	s_nop 0
	s_nop 0
	s_nop 0
	s_nop 0
	s_nop 0
	s_nop 0
	s_nop 0
	s_nop 0
	s_nop 0
	s_nop 0
	s_nop 0
	s_nop 0
	s_nop 0
	s_nop 0
	s_nop 0
	s_nop 0
	s_nop 0
	s_nop 0
	s_nop 0
	s_nop 0
	s_nop 0
	s_nop 0
	s_nop 0
	s_nop 0
	s_nop 0
	s_nop 0
	s_nop 0
	s_nop 0
	s_nop 0
	s_nop 0
	s_nop 0
	s_nop 0
	s_nop 0
	s_nop 0
	s_nop 0
	s_nop 0
	s_nop 0
	s_nop 0
	s_nop 0
	s_nop 0
	s_nop 0
	s_nop 0
	s_nop 0
	s_nop 0
	s_nop 0
	s_nop 0
	s_nop 0
	s_nop 0
	s_nop 0
	s_nop 0
	s_nop 0
	s_nop 0
	s_nop 0
	s_nop 0
	s_nop 0
	s_nop 0
	s_nop 0
	s_nop 0
	s_nop 0
	s_nop 0
	s_nop 0
	s_nop 0
	s_nop 0
	s_nop 0
	s_nop 0
	s_nop 0
	s_nop 0
	s_nop 0
	s_nop 0
	s_nop 0
	s_nop 0
	s_nop 0
	s_nop 0
	s_nop 0
	s_nop 0
	s_nop 0
	s_nop 0
	s_nop 0
	s_nop 0
	s_nop 0
	s_nop 0
	s_nop 0
	s_nop 0
	s_nop 0
	s_nop 0
	s_nop 0
	s_nop 0
	s_nop 0
	s_nop 0
	s_nop 0
	s_nop 0
	s_nop 0
	s_nop 0
	s_nop 0
	s_nop 0
	s_nop 0
	s_nop 0
	s_nop 0
	s_nop 0
	s_nop 0
	s_nop 0
	s_nop 0
	s_nop 0
	s_nop 0
	s_nop 0
	s_nop 0
	s_nop 0
	s_nop 0
	s_nop 0
	s_nop 0
	s_nop 0
	s_nop 0
	s_nop 0
	s_nop 0
	s_nop 0
	s_nop 0
	s_nop 0
	s_nop 0
	s_nop 0
	s_nop 0
	s_nop 0
	s_nop 0
	s_nop 0
	s_nop 0
	s_nop 0
	s_nop 0
	s_nop 0
	s_nop 0
	s_nop 0
	s_nop 0
	s_nop 0
	s_nop 0
	s_nop 0
	s_nop 0
	s_nop 0
	s_nop 0
	s_nop 0
	s_nop 0
	s_nop 0
	s_nop 0
	s_nop 0
	s_nop 0
	s_nop 0
	s_nop 0
	s_nop 0
	s_nop 0
	s_nop 0
	s_nop 0
	s_nop 0
	s_nop 0
	s_nop 0
	s_nop 0
	s_nop 0
	s_nop 0
	s_nop 0
	s_nop 0
	s_nop 0
	s_nop 0
	s_nop 0
	s_nop 0
	s_nop 0
	s_nop 0
	s_nop 0
	s_nop 0
	s_nop 0
	s_nop 0
	s_nop 0
	s_nop 0
	s_nop 0
	s_nop 0
	s_nop 0
	s_nop 0
	s_nop 0
	s_nop 0
	s_nop 0
	s_nop 0
	s_nop 0
	s_nop 0
	s_nop 0
	s_nop 0
	s_nop 0
	s_nop 0
	s_nop 0
	s_nop 0
	s_nop 0
	s_nop 0
	s_nop 0
	s_nop 0
	s_nop 0
	s_nop 0
	s_nop 0
	s_nop 0
	s_nop 0
	s_nop 0
	s_nop 0
	s_nop 0
	s_nop 0
	s_nop 0
	s_nop 0
	s_nop 0
	s_nop 0
